# speedup vs baseline: 1.0477x; 1.0207x over previous
; #define MFMA16(a, b, c) __builtin_amdgcn_mfma_f32_16x16x32_bf16((a), (b), (c), 0, 0, 0)
;   __device__ __forceinline__ float* gl() const { return (float*)(b + L::o_gl); }
; template <int BN, bool SWAP> ...
;     ...
;   auto comp = [&](int buf, auto&& mid) {
;     const bfu* as = As + buf * 128 * 72 + (wr * 64 + c15) * 72 + g * 8;
;     const bfu* bs = Bs + buf * BN * 72 + (wc * (BN / 2) + c15) * 72 + g * 8;
;     {
;       bf16x8 a0[4], b0[NJ];
; #pragma unroll
;       for (int i = 0; i < 4; ++i) a0[i] = *(const bf16x8*)(as + i * 16 * 72);
; #pragma unroll
;       for (int j = 0; j < NJ; ++j) b0[j] = *(const bf16x8*)(bs + j * 16 * 72);
;       mid();
;       __builtin_amdgcn_s_setprio(1);
; #pragma unroll
;       for (int i = 0; i < 4; ++i)
; #pragma unroll
;         for (int j = 0; j < NJ; ++j) acc[i][j] = SWAP ? MFMA16(b0[j], a0[i], acc[i][j]) : MFMA16(a0[i], b0[j], acc[i][j]);
;       __builtin_amdgcn_s_setprio(0);
;     }
;     {
;       bf16x8 a1[4], b1[NJ];
; #pragma unroll
;       for (int i = 0; i < 4; ++i) a1[i] = *(const bf16x8*)(as + i * 16 * 72 + 32);
; #pragma unroll
;       for (int j = 0; j < NJ; ++j) b1[j] = *(const bf16x8*)(bs + j * 16 * 72 + 32);
;       __builtin_amdgcn_s_setprio(1);
; #pragma unroll
;       for (int i = 0; i < 4; ++i)
; #pragma unroll
;         for (int j = 0; j < NJ; ++j) acc[i][j] = SWAP ? MFMA16(b1[j], a1[i], acc[i][j]) : MFMA16(a1[i], b1[j], acc[i][j]);
;       __builtin_amdgcn_s_setprio(0);
;     }
;   };
;   gl(ra0, rb0, 0);
;   gl(ra1, rb1, 1);
;   __syncthreads();
;   wt(ra0, rb0);
;   st(ra0, rb0, 0);
;   __syncthreads();
;   for (int kt = 0; kt < nk; kt += 2) {
;     gl(ra0, rb0, kt + 2);
;     comp(0, [&]() { wt(ra1, rb1); st(ra1, rb1, 1); });
;     __syncthreads();
;     gl(ra1, rb1, kt + 3);
;     comp(1, [&]() { wt(ra0, rb0); st(ra0, rb0, 0); });
;     __syncthreads();
.LBB0_110:
	s_add_i32 s27, s17, 2
	s_cmp_lt_u32 s17, 30
	s_cselect_b64 s[0:1], -1, 0
	s_add_i32 s2, s15, 0x400
	s_and_b64 s[28:29], s[10:11], exec
	s_cselect_b32 s28, 0x3e0, s15
	s_and_b64 vcc, s[0:1], exec
	s_cselect_b32 s2, s2, s28
	v_cndmask_b32_e64 v185, v157, v165, s[0:1]
	v_cndmask_b32_e64 v184, v152, v164, s[0:1]
	v_cndmask_b32_e64 v187, v159, v167, s[0:1]
	v_cndmask_b32_e64 v186, v170, v166, s[0:1]
	s_lshl_b64 s[0:1], s[2:3], 1
	v_lshl_add_u64 v[208:209], v[184:185], 0, s[0:1]
	v_lshl_add_u64 v[216:217], v[186:187], 0, s[0:1]
	ds_read_b128 v[220:223], v199 offset:40960
	ds_read_b128 v[224:227], v199 offset:42240
	ds_read_b128 v[228:231], v199 offset:43520
	ds_read_b128 v[232:235], v199 offset:44800
	ds_read_b128 v[236:239], v172
	ds_read_b128 v[240:243], v172 offset:1280
	ds_read_b128 v[244:247], v172 offset:2560
	ds_read_b128 v[248:251], v172 offset:3840
	s_waitcnt vmcnt(0)
	ds_write_b128 v168, v[128:131] offset:20480
	ds_write_b128 v168, v[132:135] offset:25600
	ds_write_b128 v168, v[136:139] offset:30720
	ds_write_b128 v168, v[140:143] offset:35840
	ds_write_b128 v169, v[144:147] offset:51200
	ds_write_b128 v169, v[148:151] offset:56320
	s_cmp_lt_u32 s17, 29
	s_cselect_b64 s[0:1], -1, 0
	s_add_i32 s2, s15, 0x420
	s_add_i32 s17, s15, 32
	s_and_b64 s[28:29], s[10:11], exec
	s_cselect_b32 s17, 0x3e0, s17
	s_and_b64 s[28:29], s[0:1], exec
	s_cselect_b32 s2, s2, s17
	v_cndmask_b32_e64 v129, v157, v165, s[0:1]
	v_cndmask_b32_e64 v128, v152, v164, s[0:1]
	v_cndmask_b32_e64 v131, v159, v167, s[0:1]
	v_cndmask_b32_e64 v130, v170, v166, s[0:1]
	s_lshl_b64 s[0:1], s[2:3], 1
	v_lshl_add_u64 v[140:141], v[128:129], 0, s[0:1]
	v_lshl_add_u64 v[148:149], v[130:131], 0, s[0:1]
	s_setprio 1
	s_waitcnt lgkmcnt(9)
	v_mfma_f32_16x16x32_bf16 v[124:127], v[220:223], v[236:239], v[124:127]
	global_load_dwordx4 v[184:187], v[208:209], off
	v_mfma_f32_16x16x32_bf16 v[120:123], v[224:227], v[236:239], v[120:123]
	global_load_dwordx4 v[128:131], v[140:141], off
	v_mfma_f32_16x16x32_bf16 v[116:119], v[228:231], v[236:239], v[116:119]
	v_lshl_add_u64 v[200:201], v[208:209], 0, s[8:9]
	global_load_dwordx4 v[200:203], v[200:201], off
	v_mfma_f32_16x16x32_bf16 v[112:115], v[232:235], v[236:239], v[112:115]
	v_lshl_add_u64 v[132:133], v[140:141], 0, s[8:9]
	global_load_dwordx4 v[132:135], v[132:133], off
	s_waitcnt lgkmcnt(8)
	v_mfma_f32_16x16x32_bf16 v[108:111], v[220:223], v[240:243], v[108:111]
	v_lshl_add_u64 v[204:205], v[208:209], 0, s[4:5]
	global_load_dwordx4 v[204:207], v[204:205], off
	v_mfma_f32_16x16x32_bf16 v[104:107], v[224:227], v[240:243], v[104:107]
	v_lshl_add_u64 v[136:137], v[140:141], 0, s[4:5]
	global_load_dwordx4 v[136:139], v[136:137], off
	v_mfma_f32_16x16x32_bf16 v[100:103], v[228:231], v[240:243], v[100:103]
	v_lshl_add_u64 v[208:209], v[208:209], 0, s[90:91]
	global_load_dwordx4 v[208:211], v[208:209], off
	v_mfma_f32_16x16x32_bf16 v[96:99], v[232:235], v[240:243], v[96:99]
	v_lshl_add_u64 v[140:141], v[140:141], 0, s[90:91]
	global_load_dwordx4 v[140:143], v[140:141], off
	s_waitcnt lgkmcnt(7)
	v_mfma_f32_16x16x32_bf16 v[92:95], v[220:223], v[244:247], v[92:95]
	global_load_dwordx4 v[212:215], v[216:217], off
	v_mfma_f32_16x16x32_bf16 v[88:91], v[224:227], v[244:247], v[88:91]
	global_load_dwordx4 v[144:147], v[148:149], off
	v_mfma_f32_16x16x32_bf16 v[84:87], v[228:231], v[244:247], v[84:87]
	v_lshl_add_u64 v[216:217], v[216:217], 0, s[8:9]
	global_load_dwordx4 v[216:219], v[216:217], off
	v_mfma_f32_16x16x32_bf16 v[80:83], v[232:235], v[244:247], v[80:83]
	v_lshl_add_u64 v[148:149], v[148:149], 0, s[8:9]
	global_load_dwordx4 v[148:151], v[148:149], off
	s_waitcnt lgkmcnt(6)
	v_mfma_f32_16x16x32_bf16 v[76:79], v[220:223], v[248:251], v[76:79]
	v_mfma_f32_16x16x32_bf16 v[72:75], v[224:227], v[248:251], v[72:75]
	v_mfma_f32_16x16x32_bf16 v[68:71], v[228:231], v[248:251], v[68:71]
	v_mfma_f32_16x16x32_bf16 v[64:67], v[232:235], v[248:251], v[64:67]
	s_setprio 0
	ds_read_b128 v[236:239], v172 offset:5120
	ds_read_b128 v[240:243], v172 offset:6400
	ds_read_b128 v[244:247], v172 offset:7680
	ds_read_b128 v[248:251], v172 offset:8960
	s_setprio 1
	s_waitcnt lgkmcnt(3)
	v_mfma_f32_16x16x32_bf16 v[60:63], v[220:223], v[236:239], v[60:63]
	v_mfma_f32_16x16x32_bf16 v[56:59], v[224:227], v[236:239], v[56:59]
	v_mfma_f32_16x16x32_bf16 v[52:55], v[228:231], v[236:239], v[52:55]
	v_mfma_f32_16x16x32_bf16 v[48:51], v[232:235], v[236:239], v[48:51]
	s_waitcnt lgkmcnt(2)
	v_mfma_f32_16x16x32_bf16 v[44:47], v[220:223], v[240:243], v[44:47]
	v_mfma_f32_16x16x32_bf16 v[40:43], v[224:227], v[240:243], v[40:43]
	v_mfma_f32_16x16x32_bf16 v[36:39], v[228:231], v[240:243], v[36:39]
	v_mfma_f32_16x16x32_bf16 v[32:35], v[232:235], v[240:243], v[32:35]
	s_waitcnt lgkmcnt(1)
	v_mfma_f32_16x16x32_bf16 v[28:31], v[220:223], v[244:247], v[28:31]
	v_mfma_f32_16x16x32_bf16 v[24:27], v[224:227], v[244:247], v[24:27]
	v_mfma_f32_16x16x32_bf16 v[20:23], v[228:231], v[244:247], v[20:23]
	v_mfma_f32_16x16x32_bf16 v[16:19], v[232:235], v[244:247], v[16:19]
	s_waitcnt lgkmcnt(0)
	v_mfma_f32_16x16x32_bf16 v[12:15], v[220:223], v[248:251], v[12:15]
	v_mfma_f32_16x16x32_bf16 v[8:11], v[224:227], v[248:251], v[8:11]
	v_mfma_f32_16x16x32_bf16 v[4:7], v[228:231], v[248:251], v[4:7]
	v_mfma_f32_16x16x32_bf16 v[0:3], v[232:235], v[248:251], v[0:3]
	s_setprio 0
	s_barrier
; #define MFMA16(a, b, c) __builtin_amdgcn_mfma_f32_16x16x32_bf16((a), (b), (c), 0, 0, 0)
;   __device__ __forceinline__ float* small() const { return (float*)(b + L::o_small); }
;   __device__ __forceinline__ float* gl() const { return (float*)(b + L::o_gl); }
; template <int BN, bool SWAP> ...
;     ...
;     {
;       bf16x8 a1[4], b1[NJ];
; #pragma unroll
;       for (int i = 0; i < 4; ++i) a1[i] = *(const bf16x8*)(as + i * 16 * 72 + 32);
; #pragma unroll
;       for (int j = 0; j < NJ; ++j) b1[j] = *(const bf16x8*)(bs + j * 16 * 72 + 32);
;       __builtin_amdgcn_s_setprio(1);
; #pragma unroll
;       for (int i = 0; i < 4; ++i)
; #pragma unroll
;         for (int j = 0; j < NJ; ++j) acc[i][j] = SWAP ? MFMA16(b1[j], a1[i], acc[i][j]) : MFMA16(a1[i], b1[j], acc[i][j]);
;       __builtin_amdgcn_s_setprio(0);
;     }
;   };
;   gl(ra0, rb0, 0);
;   gl(ra1, rb1, 1);
;   __syncthreads();
;   wt(ra0, rb0);
;   st(ra0, rb0, 0);
;   __syncthreads();
;   for (int kt = 0; kt < nk; kt += 2) {
;     gl(ra0, rb0, kt + 2);
;     comp(0, [&]() { wt(ra1, rb1); st(ra1, rb1, 1); });
;     __syncthreads();
;     gl(ra1, rb1, kt + 3);
;     comp(1, [&]() { wt(ra0, rb0); st(ra0, rb0, 0); });
;     __syncthreads();
;   }
;   if (NJ == 4) asm volatile("s_waitcnt vmcnt(0)" : "+v"(ra1[0]), "+v"(ra1[1]), "+v"(ra1[2]), "+v"(ra1[3]), "+v"(rb1[0]), "+v"(rb1[1]), "+v"(rb1[NJ - 2]), "+v"(rb1[NJ - 1]) : : "memory");
;   else asm volatile("s_waitcnt vmcnt(0)" : "+v"(ra1[0]), "+v"(ra1[1]), "+v"(ra1[2]), "+v"(ra1[3]), "+v"(rb1[0]), "+v"(rb1[1]) : : "memory");
; template <int G>
; __device__ __forceinline__ void p1_big(const Params& P, const Ptrs<G>& w, int layer, int mt, int nt, bfu* sm, int mtn, int ntn) {
;     ...
;     } else {
;       if (wc == 0 && g == 0) {
; #pragma unroll
;         for (int i = 0; i < 8; ++i) {
;           float* sp = w.small() + (size_t)(m0 + wr * 128 + 16 * i + c15) * 16;
; #pragma unroll
;           for (int j = 0; j < 4; ++j) *(float4*)(sp + 4 * j) = make_float4(acc[i][j][0], acc[i][j][1], acc[i][j][2], acc[i][j][3]);
;         }
;       }
	ds_read_b128 v[220:223], v199 offset:51200
	ds_read_b128 v[224:227], v199 offset:52480
	ds_read_b128 v[228:231], v199 offset:53760
	ds_read_b128 v[232:235], v199 offset:55040
	ds_read_b128 v[236:239], v172 offset:20480
	ds_read_b128 v[240:243], v172 offset:21760
	ds_read_b128 v[244:247], v172 offset:23040
	ds_read_b128 v[248:251], v172 offset:24320
	s_setprio 1
	s_waitcnt lgkmcnt(3)
	v_mfma_f32_16x16x32_bf16 v[124:127], v[220:223], v[236:239], v[124:127]
	v_mfma_f32_16x16x32_bf16 v[120:123], v[224:227], v[236:239], v[120:123]
	v_mfma_f32_16x16x32_bf16 v[116:119], v[228:231], v[236:239], v[116:119]
	v_mfma_f32_16x16x32_bf16 v[112:115], v[232:235], v[236:239], v[112:115]
	s_waitcnt lgkmcnt(2)
	v_mfma_f32_16x16x32_bf16 v[108:111], v[220:223], v[240:243], v[108:111]
	v_mfma_f32_16x16x32_bf16 v[104:107], v[224:227], v[240:243], v[104:107]
	v_mfma_f32_16x16x32_bf16 v[100:103], v[228:231], v[240:243], v[100:103]
	v_mfma_f32_16x16x32_bf16 v[96:99], v[232:235], v[240:243], v[96:99]
	s_waitcnt lgkmcnt(1)
	v_mfma_f32_16x16x32_bf16 v[92:95], v[220:223], v[244:247], v[92:95]
	v_mfma_f32_16x16x32_bf16 v[88:91], v[224:227], v[244:247], v[88:91]
	v_mfma_f32_16x16x32_bf16 v[84:87], v[228:231], v[244:247], v[84:87]
	v_mfma_f32_16x16x32_bf16 v[80:83], v[232:235], v[244:247], v[80:83]
	s_waitcnt lgkmcnt(0)
	v_mfma_f32_16x16x32_bf16 v[76:79], v[220:223], v[248:251], v[76:79]
	v_mfma_f32_16x16x32_bf16 v[72:75], v[224:227], v[248:251], v[72:75]
	v_mfma_f32_16x16x32_bf16 v[68:71], v[228:231], v[248:251], v[68:71]
	v_mfma_f32_16x16x32_bf16 v[64:67], v[232:235], v[248:251], v[64:67]
	s_setprio 0
	s_waitcnt vmcnt(1)
	ds_write_b128 v168, v[184:187]
	ds_write_b128 v168, v[200:203] offset:5120
	ds_write_b128 v168, v[204:207] offset:10240
	ds_write_b128 v168, v[208:211] offset:15360
	ds_write_b128 v169, v[212:215] offset:40960
	ds_write_b128 v169, v[216:219] offset:46080
	ds_read_b128 v[236:239], v172 offset:25600
	ds_read_b128 v[240:243], v172 offset:26880
	ds_read_b128 v[244:247], v172 offset:28160
	ds_read_b128 v[248:251], v172 offset:29440
	s_setprio 1
	s_waitcnt lgkmcnt(3)
	v_mfma_f32_16x16x32_bf16 v[60:63], v[220:223], v[236:239], v[60:63]
	v_mfma_f32_16x16x32_bf16 v[56:59], v[224:227], v[236:239], v[56:59]
	v_mfma_f32_16x16x32_bf16 v[52:55], v[228:231], v[236:239], v[52:55]
	v_mfma_f32_16x16x32_bf16 v[48:51], v[232:235], v[236:239], v[48:51]
	s_waitcnt lgkmcnt(2)
	v_mfma_f32_16x16x32_bf16 v[44:47], v[220:223], v[240:243], v[44:47]
	v_mfma_f32_16x16x32_bf16 v[40:43], v[224:227], v[240:243], v[40:43]
	v_mfma_f32_16x16x32_bf16 v[36:39], v[228:231], v[240:243], v[36:39]
	v_mfma_f32_16x16x32_bf16 v[32:35], v[232:235], v[240:243], v[32:35]
	s_waitcnt lgkmcnt(1)
	v_mfma_f32_16x16x32_bf16 v[28:31], v[220:223], v[244:247], v[28:31]
	v_mfma_f32_16x16x32_bf16 v[24:27], v[224:227], v[244:247], v[24:27]
	v_mfma_f32_16x16x32_bf16 v[20:23], v[228:231], v[244:247], v[20:23]
	v_mfma_f32_16x16x32_bf16 v[16:19], v[232:235], v[244:247], v[16:19]
	s_waitcnt lgkmcnt(0)
	v_mfma_f32_16x16x32_bf16 v[12:15], v[220:223], v[248:251], v[12:15]
	v_mfma_f32_16x16x32_bf16 v[8:11], v[224:227], v[248:251], v[8:11]
	v_mfma_f32_16x16x32_bf16 v[4:7], v[228:231], v[248:251], v[4:7]
	v_mfma_f32_16x16x32_bf16 v[0:3], v[232:235], v[248:251], v[0:3]
	s_setprio 0
	s_add_i32 s15, s15, 64
	s_mov_b32 s17, s27
	s_barrier
	s_cbranch_vccnz .LBB0_110
	s_waitcnt vmcnt(0)
	s_cmpk_gt_i32 s26, 0xcff
	s_mov_b64 s[0:1], -1
	s_cbranch_scc0 .LBB0_115
	v_or_b32_e32 v128, v161, v163
	v_cmp_eq_u32_e32 vcc, 0, v128
	s_and_saveexec_b64 s[0:1], vcc
	s_cbranch_execz .LBB0_114
	v_and_b32_e32 v128, 0xffffff80, v198
	v_add_u32_e32 v128, s16, v128
	v_or_b32_e32 v128, v128, v171
	v_ashrrev_i32_e32 v129, 31, v128
	v_lshlrev_b64 v[130:131], 6, v[128:129]
	v_lshl_add_u64 v[130:131], s[62:63], 0, v[130:131]
	global_store_dwordx4 v[130:131], v[124:127], off
	global_store_dwordx4 v[130:131], v[120:123], off offset:16
	global_store_dwordx4 v[130:131], v[116:119], off offset:32
	global_store_dwordx4 v[130:131], v[112:115], off offset:48
	v_or_b32_e32 v130, 16, v128
	v_ashrrev_i32_e32 v131, 31, v130
	v_lshlrev_b64 v[130:131], 6, v[130:131]
	v_lshl_add_u64 v[130:131], s[62:63], 0, v[130:131]
	global_store_dwordx4 v[130:131], v[108:111], off
	global_store_dwordx4 v[130:131], v[104:107], off offset:16
	global_store_dwordx4 v[130:131], v[100:103], off offset:32
	global_store_dwordx4 v[130:131], v[96:99], off offset:48
	v_or_b32_e32 v130, 32, v128
	v_ashrrev_i32_e32 v131, 31, v130
	v_lshlrev_b64 v[130:131], 6, v[130:131]
	v_lshl_add_u64 v[130:131], s[62:63], 0, v[130:131]
	global_store_dwordx4 v[130:131], v[92:95], off
	global_store_dwordx4 v[130:131], v[88:91], off offset:16
	global_store_dwordx4 v[130:131], v[84:87], off offset:32
	global_store_dwordx4 v[130:131], v[80:83], off offset:48
	v_or_b32_e32 v130, 48, v128
	v_ashrrev_i32_e32 v131, 31, v130
	v_lshlrev_b64 v[130:131], 6, v[130:131]
	v_lshl_add_u64 v[130:131], s[62:63], 0, v[130:131]
	global_store_dwordx4 v[130:131], v[76:79], off
	global_store_dwordx4 v[130:131], v[72:75], off offset:16
	global_store_dwordx4 v[130:131], v[68:71], off offset:32
	global_store_dwordx4 v[130:131], v[64:67], off offset:48
	v_or_b32_e32 v130, 64, v128
	v_ashrrev_i32_e32 v131, 31, v130
	v_lshlrev_b64 v[130:131], 6, v[130:131]
	v_lshl_add_u64 v[130:131], s[62:63], 0, v[130:131]
	global_store_dwordx4 v[130:131], v[60:63], off
	global_store_dwordx4 v[130:131], v[56:59], off offset:16
	global_store_dwordx4 v[130:131], v[52:55], off offset:32
	global_store_dwordx4 v[130:131], v[48:51], off offset:48
	v_or_b32_e32 v130, 0x50, v128
	v_ashrrev_i32_e32 v131, 31, v130
	v_lshlrev_b64 v[130:131], 6, v[130:131]
	v_lshl_add_u64 v[130:131], s[62:63], 0, v[130:131]
	global_store_dwordx4 v[130:131], v[44:47], off
	global_store_dwordx4 v[130:131], v[40:43], off offset:16
	global_store_dwordx4 v[130:131], v[36:39], off offset:32
	global_store_dwordx4 v[130:131], v[32:35], off offset:48
	v_or_b32_e32 v130, 0x60, v128
	v_or_b32_e32 v128, 0x70, v128
	v_ashrrev_i32_e32 v131, 31, v130
	v_ashrrev_i32_e32 v129, 31, v128
	v_lshlrev_b64 v[130:131], 6, v[130:131]
	v_lshlrev_b64 v[128:129], 6, v[128:129]
	v_lshl_add_u64 v[130:131], s[62:63], 0, v[130:131]
	v_lshl_add_u64 v[128:129], s[62:63], 0, v[128:129]
	global_store_dwordx4 v[130:131], v[28:31], off
	global_store_dwordx4 v[130:131], v[24:27], off offset:16
	global_store_dwordx4 v[130:131], v[20:23], off offset:32
	global_store_dwordx4 v[130:131], v[16:19], off offset:48
	global_store_dwordx4 v[128:129], v[12:15], off
	global_store_dwordx4 v[128:129], v[8:11], off offset:16
	global_store_dwordx4 v[128:129], v[4:7], off offset:32
	global_store_dwordx4 v[128:129], v[0:3], off offset:48

; #define MFMA16(a, b, c) __builtin_amdgcn_mfma_f32_16x16x32_bf16((a), (b), (c), 0, 0, 0)
;   __device__ __forceinline__ float* gl() const { return (float*)(b + L::o_gl); }
; template <int BN, bool SWAP> ...
;     ...
;   auto comp = [&](int buf, auto&& mid) {
;     const bfu* as = As + buf * 128 * 72 + (wr * 64 + c15) * 72 + g * 8;
;     const bfu* bs = Bs + buf * BN * 72 + (wc * (BN / 2) + c15) * 72 + g * 8;
;     {
;       bf16x8 a0[4], b0[NJ];
; #pragma unroll
;       for (int i = 0; i < 4; ++i) a0[i] = *(const bf16x8*)(as + i * 16 * 72);
; #pragma unroll
;       for (int j = 0; j < NJ; ++j) b0[j] = *(const bf16x8*)(bs + j * 16 * 72);
;       mid();
;       __builtin_amdgcn_s_setprio(1);
; #pragma unroll
;       for (int i = 0; i < 4; ++i)
; #pragma unroll
;         for (int j = 0; j < NJ; ++j) acc[i][j] = SWAP ? MFMA16(b0[j], a0[i], acc[i][j]) : MFMA16(a0[i], b0[j], acc[i][j]);
;       __builtin_amdgcn_s_setprio(0);
;     }
;     {
;       bf16x8 a1[4], b1[NJ];
; #pragma unroll
;       for (int i = 0; i < 4; ++i) a1[i] = *(const bf16x8*)(as + i * 16 * 72 + 32);
; #pragma unroll
;       for (int j = 0; j < NJ; ++j) b1[j] = *(const bf16x8*)(bs + j * 16 * 72 + 32);
;       __builtin_amdgcn_s_setprio(1);
; #pragma unroll
;       for (int i = 0; i < 4; ++i)
; #pragma unroll
;         for (int j = 0; j < NJ; ++j) acc[i][j] = SWAP ? MFMA16(b1[j], a1[i], acc[i][j]) : MFMA16(a1[i], b1[j], acc[i][j]);
;       __builtin_amdgcn_s_setprio(0);
;     }
;   };
;   gl(ra0, rb0, 0);
;   gl(ra1, rb1, 1);
;   __syncthreads();
;   wt(ra0, rb0);
;   st(ra0, rb0, 0);
;   __syncthreads();
;   for (int kt = 0; kt < nk; kt += 2) {
;     gl(ra0, rb0, kt + 2);
;     comp(0, [&]() { wt(ra1, rb1); st(ra1, rb1, 1); });
;     __syncthreads();
;     gl(ra1, rb1, kt + 3);
;     comp(1, [&]() { wt(ra0, rb0); st(ra0, rb0, 0); });
;     __syncthreads();
.LBB0_132:
	s_add_i32 s18, s17, 2
	s_cmp_lt_u32 s17, 30
	s_cselect_b64 s[0:1], -1, 0
	s_add_i32 s2, s15, 0x400
	s_and_b64 s[20:21], s[10:11], exec
	s_cselect_b32 s19, 0x3e0, s15
	s_and_b64 vcc, s[0:1], exec
	s_cselect_b32 s2, s2, s19
	v_cndmask_b32_e64 v201, v157, v165, s[0:1]
	v_cndmask_b32_e64 v200, v152, v164, s[0:1]
	v_cndmask_b32_e64 v203, v159, v167, s[0:1]
	v_cndmask_b32_e64 v202, v170, v166, s[0:1]
	s_lshl_b64 s[0:1], s[2:3], 1
	v_lshl_add_u64 v[212:213], v[200:201], 0, s[0:1]
	v_lshl_add_u64 v[220:221], v[202:203], 0, s[0:1]
	ds_read_b128 v[224:227], v169 offset:40960
	ds_read_b128 v[228:231], v169 offset:42240
	ds_read_b128 v[232:235], v169 offset:43520
	ds_read_b128 v[236:239], v169 offset:44800
	ds_read_b128 v[240:243], v172
	ds_read_b128 v[244:247], v172 offset:1280
	ds_read_b128 v[248:251], v172 offset:2560
	ds_read_b128 v[184:187], v172 offset:3840
	s_waitcnt vmcnt(0)
	ds_write_b128 v168, v[48:51] offset:20480
	ds_write_b128 v168, v[56:59] offset:25600
	ds_write_b128 v168, v[60:63] offset:30720
	ds_write_b128 v168, v[68:71] offset:35840
	ds_write_b128 v168, v[72:75] offset:51200
	ds_write_b128 v168, v[80:83] offset:56320
	s_cmp_lt_u32 s17, 29
	s_cselect_b64 s[0:1], -1, 0
	s_add_i32 s2, s15, 0x420
	s_add_i32 s17, s15, 32
	s_and_b64 s[20:21], s[10:11], exec
	s_cselect_b32 s17, 0x3e0, s17
	s_and_b64 s[20:21], s[0:1], exec
	s_cselect_b32 s2, s2, s17
	v_cndmask_b32_e64 v49, v157, v165, s[0:1]
	v_cndmask_b32_e64 v48, v152, v164, s[0:1]
	v_cndmask_b32_e64 v51, v159, v167, s[0:1]
	v_cndmask_b32_e64 v50, v170, v166, s[0:1]
	s_lshl_b64 s[0:1], s[2:3], 1
	v_lshl_add_u64 v[68:69], v[48:49], 0, s[0:1]
	v_lshl_add_u64 v[80:81], v[50:51], 0, s[0:1]
	s_setprio 1
	s_waitcnt lgkmcnt(9)
	v_mfma_f32_16x16x32_bf16 v[148:151], v[240:243], v[224:227], v[148:151]
	global_load_dwordx4 v[200:203], v[212:213], off
	v_mfma_f32_16x16x32_bf16 v[144:147], v[240:243], v[228:231], v[144:147]
	global_load_dwordx4 v[48:51], v[68:69], off
	v_mfma_f32_16x16x32_bf16 v[140:143], v[240:243], v[232:235], v[140:143]
	v_lshl_add_u64 v[204:205], v[212:213], 0, s[8:9]
	global_load_dwordx4 v[204:207], v[204:205], off
	v_mfma_f32_16x16x32_bf16 v[136:139], v[240:243], v[236:239], v[136:139]
	v_lshl_add_u64 v[56:57], v[68:69], 0, s[8:9]
	global_load_dwordx4 v[56:59], v[56:57], off
	s_waitcnt lgkmcnt(8)
	v_mfma_f32_16x16x32_bf16 v[132:135], v[244:247], v[224:227], v[132:135]
	v_lshl_add_u64 v[208:209], v[212:213], 0, s[4:5]
	global_load_dwordx4 v[208:211], v[208:209], off
	v_mfma_f32_16x16x32_bf16 v[128:131], v[244:247], v[228:231], v[128:131]
	v_lshl_add_u64 v[60:61], v[68:69], 0, s[4:5]
	global_load_dwordx4 v[60:63], v[60:61], off
	v_mfma_f32_16x16x32_bf16 v[124:127], v[244:247], v[232:235], v[124:127]
	v_lshl_add_u64 v[212:213], v[212:213], 0, s[90:91]
	global_load_dwordx4 v[212:215], v[212:213], off
	v_mfma_f32_16x16x32_bf16 v[120:123], v[244:247], v[236:239], v[120:123]
	v_lshl_add_u64 v[68:69], v[68:69], 0, s[90:91]
	global_load_dwordx4 v[68:71], v[68:69], off
	s_waitcnt lgkmcnt(7)
	v_mfma_f32_16x16x32_bf16 v[116:119], v[248:251], v[224:227], v[116:119]
	global_load_dwordx4 v[216:219], v[220:221], off
	v_mfma_f32_16x16x32_bf16 v[112:115], v[248:251], v[228:231], v[112:115]
	global_load_dwordx4 v[72:75], v[80:81], off
	v_mfma_f32_16x16x32_bf16 v[108:111], v[248:251], v[232:235], v[108:111]
	v_lshl_add_u64 v[220:221], v[220:221], 0, s[8:9]
	global_load_dwordx4 v[220:223], v[220:221], off
	v_mfma_f32_16x16x32_bf16 v[104:107], v[248:251], v[236:239], v[104:107]
	v_lshl_add_u64 v[80:81], v[80:81], 0, s[8:9]
	global_load_dwordx4 v[80:83], v[80:81], off
	s_waitcnt lgkmcnt(6)
	v_mfma_f32_16x16x32_bf16 v[100:103], v[184:187], v[224:227], v[100:103]
	v_mfma_f32_16x16x32_bf16 v[96:99], v[184:187], v[228:231], v[96:99]
	v_mfma_f32_16x16x32_bf16 v[92:95], v[184:187], v[232:235], v[92:95]
	v_mfma_f32_16x16x32_bf16 v[88:91], v[184:187], v[236:239], v[88:91]
	s_setprio 0
	ds_read_b128 v[240:243], v172 offset:5120
	ds_read_b128 v[244:247], v172 offset:6400
	ds_read_b128 v[248:251], v172 offset:7680
	ds_read_b128 v[184:187], v172 offset:8960
	s_setprio 1
	s_waitcnt lgkmcnt(3)
	v_mfma_f32_16x16x32_bf16 v[84:87], v[240:243], v[224:227], v[84:87]
	v_mfma_f32_16x16x32_bf16 v[76:79], v[240:243], v[228:231], v[76:79]
	v_mfma_f32_16x16x32_bf16 v[64:67], v[240:243], v[232:235], v[64:67]
	v_mfma_f32_16x16x32_bf16 v[52:55], v[240:243], v[236:239], v[52:55]
	s_waitcnt lgkmcnt(2)
	v_mfma_f32_16x16x32_bf16 v[44:47], v[244:247], v[224:227], v[44:47]
	v_mfma_f32_16x16x32_bf16 v[40:43], v[244:247], v[228:231], v[40:43]
	v_mfma_f32_16x16x32_bf16 v[36:39], v[244:247], v[232:235], v[36:39]
	v_mfma_f32_16x16x32_bf16 v[32:35], v[244:247], v[236:239], v[32:35]
	s_waitcnt lgkmcnt(1)
	v_mfma_f32_16x16x32_bf16 v[28:31], v[248:251], v[224:227], v[28:31]
	v_mfma_f32_16x16x32_bf16 v[24:27], v[248:251], v[228:231], v[24:27]
	v_mfma_f32_16x16x32_bf16 v[20:23], v[248:251], v[232:235], v[20:23]
	v_mfma_f32_16x16x32_bf16 v[16:19], v[248:251], v[236:239], v[16:19]
	s_waitcnt lgkmcnt(0)
	v_mfma_f32_16x16x32_bf16 v[12:15], v[184:187], v[224:227], v[12:15]
	v_mfma_f32_16x16x32_bf16 v[8:11], v[184:187], v[228:231], v[8:11]
	v_mfma_f32_16x16x32_bf16 v[4:7], v[184:187], v[232:235], v[4:7]
	v_mfma_f32_16x16x32_bf16 v[0:3], v[184:187], v[236:239], v[0:3]
	s_setprio 0
	s_barrier
; #define MFMA16(a, b, c) __builtin_amdgcn_mfma_f32_16x16x32_bf16((a), (b), (c), 0, 0, 0)
;   __device__ __forceinline__ float* gl() const { return (float*)(b + L::o_gl); }
; template <int BN, bool SWAP> ...
;     ...
;     {
;       bf16x8 a1[4], b1[NJ];
; #pragma unroll
;       for (int i = 0; i < 4; ++i) a1[i] = *(const bf16x8*)(as + i * 16 * 72 + 32);
; #pragma unroll
;       for (int j = 0; j < NJ; ++j) b1[j] = *(const bf16x8*)(bs + j * 16 * 72 + 32);
;       __builtin_amdgcn_s_setprio(1);
; #pragma unroll
;       for (int i = 0; i < 4; ++i)
; #pragma unroll
;         for (int j = 0; j < NJ; ++j) acc[i][j] = SWAP ? MFMA16(b1[j], a1[i], acc[i][j]) : MFMA16(a1[i], b1[j], acc[i][j]);
;       __builtin_amdgcn_s_setprio(0);
;     }
;   };
;   gl(ra0, rb0, 0);
;   gl(ra1, rb1, 1);
;   __syncthreads();
;   wt(ra0, rb0);
;   st(ra0, rb0, 0);
;   __syncthreads();
;   for (int kt = 0; kt < nk; kt += 2) {
;     gl(ra0, rb0, kt + 2);
;     comp(0, [&]() { wt(ra1, rb1); st(ra1, rb1, 1); });
;     __syncthreads();
;     gl(ra1, rb1, kt + 3);
;     comp(1, [&]() { wt(ra0, rb0); st(ra0, rb0, 0); });
;     __syncthreads();
;   }
	ds_read_b128 v[184:187], v169 offset:51200
	ds_read_b128 v[224:227], v169 offset:52480
	ds_read_b128 v[228:231], v169 offset:53760
	ds_read_b128 v[232:235], v169 offset:55040
	ds_read_b128 v[236:239], v172 offset:20480
	ds_read_b128 v[240:243], v172 offset:21760
	ds_read_b128 v[244:247], v172 offset:23040
	ds_read_b128 v[248:251], v172 offset:24320
	s_setprio 1
	s_waitcnt lgkmcnt(3)
	v_mfma_f32_16x16x32_bf16 v[148:151], v[236:239], v[184:187], v[148:151]
	v_mfma_f32_16x16x32_bf16 v[144:147], v[236:239], v[224:227], v[144:147]
	v_mfma_f32_16x16x32_bf16 v[140:143], v[236:239], v[228:231], v[140:143]
	v_mfma_f32_16x16x32_bf16 v[136:139], v[236:239], v[232:235], v[136:139]
	s_waitcnt lgkmcnt(2)
	v_mfma_f32_16x16x32_bf16 v[132:135], v[240:243], v[184:187], v[132:135]
	v_mfma_f32_16x16x32_bf16 v[128:131], v[240:243], v[224:227], v[128:131]
	v_mfma_f32_16x16x32_bf16 v[124:127], v[240:243], v[228:231], v[124:127]
	v_mfma_f32_16x16x32_bf16 v[120:123], v[240:243], v[232:235], v[120:123]
	s_waitcnt lgkmcnt(1)
	v_mfma_f32_16x16x32_bf16 v[116:119], v[244:247], v[184:187], v[116:119]
	v_mfma_f32_16x16x32_bf16 v[112:115], v[244:247], v[224:227], v[112:115]
	v_mfma_f32_16x16x32_bf16 v[108:111], v[244:247], v[228:231], v[108:111]
	v_mfma_f32_16x16x32_bf16 v[104:107], v[244:247], v[232:235], v[104:107]
	s_waitcnt lgkmcnt(0)
	v_mfma_f32_16x16x32_bf16 v[100:103], v[248:251], v[184:187], v[100:103]
	v_mfma_f32_16x16x32_bf16 v[96:99], v[248:251], v[224:227], v[96:99]
	v_mfma_f32_16x16x32_bf16 v[92:95], v[248:251], v[228:231], v[92:95]
	v_mfma_f32_16x16x32_bf16 v[88:91], v[248:251], v[232:235], v[88:91]
	s_setprio 0
	s_waitcnt vmcnt(1)
	ds_write_b128 v168, v[200:203]
	ds_write_b128 v168, v[204:207] offset:5120
	ds_write_b128 v168, v[208:211] offset:10240
	ds_write_b128 v168, v[212:215] offset:15360
	ds_write_b128 v168, v[216:219] offset:40960
	ds_write_b128 v168, v[220:223] offset:46080
	ds_read_b128 v[236:239], v172 offset:25600
	ds_read_b128 v[240:243], v172 offset:26880
	ds_read_b128 v[244:247], v172 offset:28160
	ds_read_b128 v[248:251], v172 offset:29440
	s_setprio 1
	s_waitcnt lgkmcnt(3)
	v_mfma_f32_16x16x32_bf16 v[84:87], v[236:239], v[184:187], v[84:87]
	v_mfma_f32_16x16x32_bf16 v[76:79], v[236:239], v[224:227], v[76:79]
	v_mfma_f32_16x16x32_bf16 v[64:67], v[236:239], v[228:231], v[64:67]
	v_mfma_f32_16x16x32_bf16 v[52:55], v[236:239], v[232:235], v[52:55]
	s_waitcnt lgkmcnt(2)
	v_mfma_f32_16x16x32_bf16 v[44:47], v[240:243], v[184:187], v[44:47]
	v_mfma_f32_16x16x32_bf16 v[40:43], v[240:243], v[224:227], v[40:43]
	v_mfma_f32_16x16x32_bf16 v[36:39], v[240:243], v[228:231], v[36:39]
	v_mfma_f32_16x16x32_bf16 v[32:35], v[240:243], v[232:235], v[32:35]
	s_waitcnt lgkmcnt(1)
	v_mfma_f32_16x16x32_bf16 v[28:31], v[244:247], v[184:187], v[28:31]
	v_mfma_f32_16x16x32_bf16 v[24:27], v[244:247], v[224:227], v[24:27]
	v_mfma_f32_16x16x32_bf16 v[20:23], v[244:247], v[228:231], v[20:23]
	v_mfma_f32_16x16x32_bf16 v[16:19], v[244:247], v[232:235], v[16:19]
	s_waitcnt lgkmcnt(0)
	v_mfma_f32_16x16x32_bf16 v[12:15], v[248:251], v[184:187], v[12:15]
	v_mfma_f32_16x16x32_bf16 v[8:11], v[248:251], v[224:227], v[8:11]
	v_mfma_f32_16x16x32_bf16 v[4:7], v[248:251], v[228:231], v[4:7]
	v_mfma_f32_16x16x32_bf16 v[0:3], v[248:251], v[232:235], v[0:3]
	s_setprio 0
	s_add_i32 s15, s15, 64
	s_mov_b32 s17, s18
	s_barrier
	s_cbranch_vccnz .LBB0_132
;   __device__ __forceinline__ bfu* VtC() const { return (bfu*)(b + L::o_VtC); }
;   __device__ __forceinline__ bfu* VtD() const { return (bfu*)(b + L::o_VtD); }
;   __device__ __forceinline__ bfu* rb() const { return (bfu*)(b + L::o_rb); }
; template <int BN, bool SWAP> ...
;     ...
;   if (NJ == 4) asm volatile("s_waitcnt vmcnt(0)" : "+v"(ra1[0]), "+v"(ra1[1]), "+v"(ra1[2]), "+v"(ra1[3]), "+v"(rb1[0]), "+v"(rb1[1]), "+v"(rb1[NJ - 2]), "+v"(rb1[NJ - 1]) : : "memory");
; template <int G>
; __device__ __forceinline__ void p1_big(const Params& P, const Ptrs<G>& w, int layer, int mt, int nt, bfu* sm, int mtn, int ntn) {
;     ...
;     bfu* dst = (n0 < 7168) ? w.VtC() : w.VtD();
;     const int cofs = (n0 < 7168) ? (n0 - 6656) : (n0 - 7168);
; #pragma unroll
;     for (int i = 0; i < 8; ++i)
; #pragma unroll
;       for (int j = 0; j < 4; ++j) {
;         int rb = m0 + wr * 128 + i * 16 + g * 4; int c = cofs + wc * 64 + j * 16 + c15;
;         int seq = rb >> 13, t = rb & 8191, h = c >> 6, d = c & 63;
;         uint2 o; o.x = pack2(acc[i][j][0], acc[i][j][1]); o.y = pack2(acc[i][j][2], acc[i][j][3]);
;         *(uint2*)(dst + ((size_t)((seq * 8 + h) * 64 + d)) * TSEQ + t) = o;
;       }
	s_cmp_lt_u32 s35, 56
	s_cselect_b64 s[0:1], -1, 0
	s_waitcnt vmcnt(0)
	s_and_b64 s[0:1], s[0:1], exec
	s_movk_i32 s0, 0xe600
	v_and_b32_e32 v48, 0xffffff80, v198
	s_cselect_b32 s2, s0, 0xffffe400
	v_add_u32_e32 v48, s16, v48
	v_or_b32_e32 v50, s14, v171
	s_mov_b32 s0, 0x18121800
	v_readlane_b32 s20, v253, 38
	v_and_b32_e32 v49, 0x1f80, v48
	v_ashrrev_i32_e32 v48, 4, v48
	v_add_u32_e32 v50, s2, v50
	s_cselect_b32 s0, s0, 0x19121800
	v_readlane_b32 s22, v253, 40
	v_and_b32_e32 v48, 0xfffffe00, v48
	v_lshl_or_b32 v50, v161, 6, v50
	v_readlane_b32 s23, v253, 41
	s_add_u32 s0, s22, s0
	v_add_u32_e32 v48, v50, v48
	v_lshlrev_b32_e32 v49, 1, v49
	s_addc_u32 s1, s23, 0
	v_lshl_or_b32 v152, v163, 3, v49
	v_ashrrev_i32_e32 v49, 31, v48
	v_lshl_add_u64 v[50:51], s[0:1], 0, v[152:153]
	v_lshlrev_b64 v[56:57], 14, v[48:49]
	v_lshl_add_u64 v[56:57], v[50:51], 0, v[56:57]
	v_cvt_pk_bf16_f32 v59, v150, v151
	v_cvt_pk_bf16_f32 v58, v148, v149
	global_store_dwordx2 v[56:57], v[58:59], off
	v_or_b32_e32 v58, 16, v48
	v_ashrrev_i32_e32 v59, 31, v58
	v_lshlrev_b64 v[58:59], 14, v[58:59]
	v_lshl_add_u64 v[58:59], v[50:51], 0, v[58:59]
	v_cvt_pk_bf16_f32 v61, v146, v147
	v_cvt_pk_bf16_f32 v60, v144, v145
	global_store_dwordx2 v[58:59], v[60:61], off
	v_or_b32_e32 v60, 32, v48
	v_or_b32_e32 v48, 48, v48
	v_ashrrev_i32_e32 v61, 31, v60
	v_ashrrev_i32_e32 v49, 31, v48
	v_lshlrev_b64 v[60:61], 14, v[60:61]
	v_lshlrev_b64 v[48:49], 14, v[48:49]
	v_lshl_add_u64 v[60:61], v[50:51], 0, v[60:61]
	v_lshl_add_u64 v[48:49], v[50:51], 0, v[48:49]
	v_cvt_pk_bf16_f32 v51, v138, v139
	v_cvt_pk_bf16_f32 v50, v136, v137
	global_store_dwordx2 v[48:49], v[50:51], off
	v_cvt_pk_bf16_f32 v51, v134, v135
	v_cvt_pk_bf16_f32 v50, v132, v133
	global_store_dwordx2 v[56:57], v[50:51], off offset:32
	v_cvt_pk_bf16_f32 v51, v130, v131
	v_cvt_pk_bf16_f32 v50, v128, v129
	global_store_dwordx2 v[58:59], v[50:51], off offset:32
	v_cvt_pk_bf16_f32 v51, v126, v127
	v_cvt_pk_bf16_f32 v50, v124, v125
	global_store_dwordx2 v[60:61], v[50:51], off offset:32
	v_cvt_pk_bf16_f32 v51, v122, v123
	v_cvt_pk_bf16_f32 v50, v120, v121
	global_store_dwordx2 v[48:49], v[50:51], off offset:32
	v_cvt_pk_bf16_f32 v51, v118, v119
	v_cvt_pk_bf16_f32 v50, v116, v117
	global_store_dwordx2 v[56:57], v[50:51], off offset:64
	v_cvt_pk_bf16_f32 v51, v114, v115
	v_cvt_pk_bf16_f32 v50, v112, v113
	global_store_dwordx2 v[58:59], v[50:51], off offset:64
	v_cvt_pk_bf16_f32 v51, v110, v111
	v_cvt_pk_bf16_f32 v50, v108, v109
	global_store_dwordx2 v[60:61], v[50:51], off offset:64
	v_cvt_pk_bf16_f32 v51, v106, v107
	v_cvt_pk_bf16_f32 v50, v104, v105
	global_store_dwordx2 v[48:49], v[50:51], off offset:64
	v_cvt_pk_bf16_f32 v51, v102, v103
	v_cvt_pk_bf16_f32 v50, v100, v101
	global_store_dwordx2 v[56:57], v[50:51], off offset:96
	v_cvt_pk_bf16_f32 v51, v98, v99
	v_cvt_pk_bf16_f32 v50, v96, v97
	global_store_dwordx2 v[58:59], v[50:51], off offset:96
	v_cvt_pk_bf16_f32 v51, v94, v95
	v_cvt_pk_bf16_f32 v50, v92, v93
	global_store_dwordx2 v[60:61], v[50:51], off offset:96
	v_cvt_pk_bf16_f32 v51, v90, v91
	v_cvt_pk_bf16_f32 v50, v88, v89
	global_store_dwordx2 v[48:49], v[50:51], off offset:96
	v_cvt_pk_bf16_f32 v51, v86, v87
	v_cvt_pk_bf16_f32 v50, v84, v85
	global_store_dwordx2 v[56:57], v[50:51], off offset:128
	v_cvt_pk_bf16_f32 v51, v78, v79
	v_cvt_pk_bf16_f32 v50, v76, v77
	global_store_dwordx2 v[58:59], v[50:51], off offset:128
	v_cvt_pk_bf16_f32 v51, v66, v67
	v_cvt_pk_bf16_f32 v50, v64, v65
	v_cvt_pk_bf16_f32 v63, v142, v143
	v_cvt_pk_bf16_f32 v62, v140, v141
	global_store_dwordx2 v[60:61], v[50:51], off offset:128
	v_cvt_pk_bf16_f32 v51, v54, v55
	v_cvt_pk_bf16_f32 v50, v52, v53
	v_cvt_pk_bf16_f32 v47, v46, v47
	v_cvt_pk_bf16_f32 v46, v44, v45
	v_cvt_pk_bf16_f32 v43, v42, v43
	v_cvt_pk_bf16_f32 v42, v40, v41
	v_cvt_pk_bf16_f32 v39, v38, v39
	v_cvt_pk_bf16_f32 v38, v36, v37
	v_cvt_pk_bf16_f32 v35, v34, v35
	v_cvt_pk_bf16_f32 v34, v32, v33
	v_cvt_pk_bf16_f32 v31, v30, v31
	v_cvt_pk_bf16_f32 v30, v28, v29
	v_cvt_pk_bf16_f32 v27, v26, v27
	v_cvt_pk_bf16_f32 v26, v24, v25
	v_cvt_pk_bf16_f32 v23, v22, v23
	v_cvt_pk_bf16_f32 v22, v20, v21
	v_cvt_pk_bf16_f32 v19, v18, v19
	v_cvt_pk_bf16_f32 v18, v16, v17
	v_cvt_pk_bf16_f32 v15, v14, v15
	v_cvt_pk_bf16_f32 v14, v12, v13
	v_cvt_pk_bf16_f32 v11, v10, v11
	v_cvt_pk_bf16_f32 v10, v8, v9
	v_cvt_pk_bf16_f32 v7, v6, v7
	v_cvt_pk_bf16_f32 v6, v4, v5
	v_cvt_pk_bf16_f32 v3, v2, v3
	v_cvt_pk_bf16_f32 v2, v0, v1
	v_readlane_b32 s21, v253, 39
	global_store_dwordx2 v[60:61], v[62:63], off
	global_store_dwordx2 v[48:49], v[50:51], off offset:128
	global_store_dwordx2 v[56:57], v[46:47], off offset:160
	global_store_dwordx2 v[58:59], v[42:43], off offset:160
	global_store_dwordx2 v[60:61], v[38:39], off offset:160
	global_store_dwordx2 v[48:49], v[34:35], off offset:160
	global_store_dwordx2 v[56:57], v[30:31], off offset:192
	global_store_dwordx2 v[58:59], v[26:27], off offset:192
	global_store_dwordx2 v[60:61], v[22:23], off offset:192
	global_store_dwordx2 v[48:49], v[18:19], off offset:192
	global_store_dwordx2 v[56:57], v[14:15], off offset:224
	global_store_dwordx2 v[58:59], v[10:11], off offset:224
	global_store_dwordx2 v[60:61], v[6:7], off offset:224
	global_store_dwordx2 v[48:49], v[2:3], off offset:224
	s_branch .LBB0_106

; __device__ __forceinline__ float bf2f(bfu h) { return __uint_as_float(((unsigned)h) << 16); }
; __device__ __forceinline__ float sigm(float x) { return 1.f / (1.f + __expf(-x)); }
;   __device__ __forceinline__ bfu* glu() const { return (bfu*)(b + L::o_glu); }
; template <int G>
; __device__ __forceinline__ void p2_conformer(const Params& P, const Ptrs<G>& w, int layer, int item, float* cv, int kslot) {
;     ...
;     float wj[31], a[32];
;     const float* cw = P.conv_dw + (size_t)layer * 31 * 512 + c;
; #pragma unroll
;     for (int j = 0; j < 31; ++j) wj[j] = cw[j * 512];
;     const float b0 = P.conv_dw_bias[layer * 512 + c];
; #pragma unroll
;     for (int t = 0; t < 32; ++t) a[t] = b0;
; #pragma unroll
;     for (int sr = 0; sr < 62; ++sr) {
;       const int s = t0 - 30 + sr;
;       float h0 = 0.f;
;       if (s >= 0) {
;         const bfu* gp = w.glu() + (seqbase + s) * 1024 + c;
;         h0 = bf2f(gp[0]) * sigm(bf2f(gp[512]));
;       }
.LBB0_349:
	v_add_u32_e32 v2, s72, v16
	v_ashrrev_i32_e32 v3, 31, v2
	v_lshl_add_u64 v[4:5], v[2:3], 2, s[12:13]
	v_add_co_u32_e32 v6, vcc, 0x1000, v4
	global_load_dword v68, v[4:5], off
	global_load_dword v67, v[4:5], off offset:2048
	v_addc_co_u32_e32 v7, vcc, 0, v5, vcc
	global_load_dword v66, v[6:7], off
	global_load_dword v65, v[6:7], off offset:2048
	v_add_co_u32_e32 v6, vcc, 0x2000, v4
	v_readlane_b32 s10, v252, 38
	s_nop 0
	v_addc_co_u32_e32 v7, vcc, 0, v5, vcc
	global_load_dword v64, v[6:7], off
	global_load_dword v63, v[6:7], off offset:2048
	v_add_co_u32_e32 v6, vcc, 0x3000, v4
	v_readlane_b32 s11, v252, 39
	s_nop 0
	v_addc_co_u32_e32 v7, vcc, 0, v5, vcc
	global_load_dword v62, v[6:7], off
	global_load_dword v61, v[6:7], off offset:2048
	v_add_co_u32_e32 v6, vcc, 0x4000, v4
	v_mov_b32_e32 v8, 0
	s_nop 0
	v_addc_co_u32_e32 v7, vcc, 0, v5, vcc
	global_load_dword v60, v[6:7], off
	global_load_dword v59, v[6:7], off offset:2048
	v_add_co_u32_e32 v6, vcc, 0x5000, v4
	s_nop 1
	v_addc_co_u32_e32 v7, vcc, 0, v5, vcc
	global_load_dword v58, v[6:7], off
	global_load_dword v57, v[6:7], off offset:2048
	v_add_co_u32_e32 v6, vcc, s16, v4
	v_readlane_b32 s16, v252, 10
	s_nop 0
	v_addc_co_u32_e32 v7, vcc, 0, v5, vcc
	global_load_dword v56, v[6:7], off
	global_load_dword v55, v[6:7], off offset:2048
	v_add_co_u32_e32 v6, vcc, 0x7000, v4
	v_readlane_b32 s18, v252, 12
	s_nop 0
	v_addc_co_u32_e32 v7, vcc, 0, v5, vcc
	global_load_dword v54, v[6:7], off
	global_load_dword v53, v[6:7], off offset:2048
	v_add_co_u32_e32 v6, vcc, s88, v4
	v_readlane_b32 s19, v252, 13
	s_nop 0
	v_addc_co_u32_e32 v7, vcc, 0, v5, vcc
	global_load_dword v52, v[6:7], off
	global_load_dword v51, v[6:7], off offset:2048
	v_add_co_u32_e32 v6, vcc, 0x9000, v4
	v_readlane_b32 s17, v252, 11
	s_nop 0
	v_addc_co_u32_e32 v7, vcc, 0, v5, vcc
	global_load_dword v50, v[6:7], off
	global_load_dword v49, v[6:7], off offset:2048
	v_add_co_u32_e32 v6, vcc, 0xa000, v4
	v_readlane_b32 s20, v252, 14
	s_nop 0
	v_addc_co_u32_e32 v7, vcc, 0, v5, vcc
	global_load_dword v48, v[6:7], off
	global_load_dword v46, v[6:7], off offset:2048
	v_add_co_u32_e32 v6, vcc, 0xb000, v4
	v_readlane_b32 s21, v252, 15
	s_nop 0
	v_addc_co_u32_e32 v7, vcc, 0, v5, vcc
	global_load_dword v47, v[6:7], off
	global_load_dword v45, v[6:7], off offset:2048
	v_add_co_u32_e32 v6, vcc, 0xc000, v4
	v_readlane_b32 s22, v252, 16
	s_nop 0
	v_addc_co_u32_e32 v7, vcc, 0, v5, vcc
	global_load_dword v44, v[6:7], off
	global_load_dword v43, v[6:7], off offset:2048
	v_add_co_u32_e32 v6, vcc, 0xd000, v4
	v_readlane_b32 s23, v252, 17
	s_nop 0
	v_addc_co_u32_e32 v7, vcc, 0, v5, vcc
	global_load_dword v42, v[6:7], off
	global_load_dword v41, v[6:7], off offset:2048
	v_add_co_u32_e32 v6, vcc, 0xe000, v4
	v_readlane_b32 s24, v252, 18
	s_nop 0
	v_addc_co_u32_e32 v7, vcc, 0, v5, vcc
	v_add_co_u32_e32 v4, vcc, 0xf000, v4
	global_load_dword v40, v[6:7], off
	global_load_dword v39, v[6:7], off offset:2048
	v_addc_co_u32_e32 v5, vcc, 0, v5, vcc
	global_load_dword v6, v[4:5], off
	v_add_u32_e32 v4, s94, v2
	v_ashrrev_i32_e32 v5, 31, v4
	v_lshl_add_u64 v[4:5], v[4:5], 2, s[18:19]
	global_load_dword v7, v[4:5], off
	v_lshl_add_u64 v[4:5], v[2:3], 1, s[10:11]
	s_and_b64 vcc, exec, s[14:15]
	s_cbranch_vccz .Lcpf_skip
	v_readlane_b32 s16, v254, 53
	v_readlane_b32 s17, v254, 54
	s_nop 1
	v_lshl_add_u64 v[10:11], v[4:5], 0, s[16:17]
	s_mov_b64 s[16:17], 0x1000
	v_lshl_add_u64 v[10:11], v[10:11], 0, s[16:17]
	s_mov_b64 s[16:17], 0x2000
	global_load_ushort v8, v[10:11], off offset:-4096
	global_load_ushort v8, v[10:11], off offset:-3072
	global_load_ushort v8, v[10:11], off offset:-2048
	global_load_ushort v8, v[10:11], off offset:-1024
	global_load_ushort v8, v[10:11], off
	global_load_ushort v8, v[10:11], off offset:1024
	global_load_ushort v8, v[10:11], off offset:2048
	global_load_ushort v8, v[10:11], off offset:3072
	v_lshl_add_u64 v[10:11], v[10:11], 0, s[16:17]
	global_load_ushort v8, v[10:11], off offset:-4096
	global_load_ushort v8, v[10:11], off offset:-3072
	global_load_ushort v8, v[10:11], off offset:-2048
	global_load_ushort v8, v[10:11], off offset:-1024
	global_load_ushort v8, v[10:11], off
	global_load_ushort v8, v[10:11], off offset:1024
	global_load_ushort v8, v[10:11], off offset:2048
	global_load_ushort v8, v[10:11], off offset:3072
	v_lshl_add_u64 v[10:11], v[10:11], 0, s[16:17]
	global_load_ushort v8, v[10:11], off offset:-4096
	global_load_ushort v8, v[10:11], off offset:-3072
	global_load_ushort v8, v[10:11], off offset:-2048
	global_load_ushort v8, v[10:11], off offset:-1024
	global_load_ushort v8, v[10:11], off
	global_load_ushort v8, v[10:11], off offset:1024
	global_load_ushort v8, v[10:11], off offset:2048
	global_load_ushort v8, v[10:11], off offset:3072
	v_lshl_add_u64 v[10:11], v[10:11], 0, s[16:17]
	global_load_ushort v8, v[10:11], off offset:-4096
	global_load_ushort v8, v[10:11], off offset:-3072
	global_load_ushort v8, v[10:11], off offset:-2048
	global_load_ushort v8, v[10:11], off offset:-1024
	global_load_ushort v8, v[10:11], off
	global_load_ushort v8, v[10:11], off offset:1024
	global_load_ushort v8, v[10:11], off offset:2048
	global_load_ushort v8, v[10:11], off offset:3072
	v_lshl_add_u64 v[10:11], v[10:11], 0, s[16:17]
	global_load_ushort v8, v[10:11], off offset:-4096
	global_load_ushort v8, v[10:11], off offset:-3072
	global_load_ushort v8, v[10:11], off offset:-2048
	global_load_ushort v8, v[10:11], off offset:-1024
	global_load_ushort v8, v[10:11], off
	global_load_ushort v8, v[10:11], off offset:1024
	global_load_ushort v8, v[10:11], off offset:2048
	global_load_ushort v8, v[10:11], off offset:3072
; __device__ __forceinline__ float bf2f(bfu h) { return __uint_as_float(((unsigned)h) << 16); }
; __device__ __forceinline__ float sigm(float x) { return 1.f / (1.f + __expf(-x)); }
;   __device__ __forceinline__ bfu* glu() const { return (bfu*)(b + L::o_glu); }
; template <int G>
; __device__ __forceinline__ void p2_conformer(const Params& P, const Ptrs<G>& w, int layer, int item, float* cv, int kslot) {
;     ...
;     for (int sr = 0; sr < 62; ++sr) {
;       const int s = t0 - 30 + sr;
;       float h0 = 0.f;
;       if (s >= 0) {
;         const bfu* gp = w.glu() + (seqbase + s) * 1024 + c;
;         h0 = bf2f(gp[0]) * sigm(bf2f(gp[512]));
;       }
; #pragma unroll
;       for (int tr = 0; tr < 32; ++tr) {
;         const int j = sr - tr;
;         if (j >= 0 && j <= 30) a[tr] += wj[j] * h0;
;       }
;     }
	v_lshl_add_u64 v[10:11], v[10:11], 0, s[16:17]
	global_load_ushort v8, v[10:11], off offset:-4096
	global_load_ushort v8, v[10:11], off offset:-3072
	global_load_ushort v8, v[10:11], off offset:-2048
	global_load_ushort v8, v[10:11], off offset:-1024
	global_load_ushort v8, v[10:11], off
	global_load_ushort v8, v[10:11], off offset:1024
	global_load_ushort v8, v[10:11], off offset:2048
	global_load_ushort v8, v[10:11], off offset:3072
	v_lshl_add_u64 v[10:11], v[10:11], 0, s[16:17]
	global_load_ushort v8, v[10:11], off offset:-4096
	global_load_ushort v8, v[10:11], off offset:-3072
	global_load_ushort v8, v[10:11], off offset:-2048
	global_load_ushort v8, v[10:11], off offset:-1024
	global_load_ushort v8, v[10:11], off
	global_load_ushort v8, v[10:11], off offset:1024
	global_load_ushort v8, v[10:11], off offset:2048
	global_load_ushort v8, v[10:11], off offset:3072
	v_lshl_add_u64 v[10:11], v[10:11], 0, s[16:17]
	global_load_ushort v8, v[10:11], off offset:-4096
	global_load_ushort v8, v[10:11], off offset:-3072
	global_load_ushort v8, v[10:11], off offset:-2048
	global_load_ushort v8, v[10:11], off offset:-1024
	global_load_ushort v8, v[10:11], off
	global_load_ushort v8, v[10:11], off offset:1024
	global_load_ushort v8, v[10:11], off offset:2048
	global_load_ushort v8, v[10:11], off offset:3072
	v_lshl_add_u64 v[10:11], v[10:11], 0, s[16:17]
	global_load_ushort v8, v[10:11], off offset:-4096
	global_load_ushort v8, v[10:11], off offset:-3072
	global_load_ushort v8, v[10:11], off offset:-2048
	global_load_ushort v8, v[10:11], off offset:-1024
	global_load_ushort v8, v[10:11], off
	global_load_ushort v8, v[10:11], off offset:1024
	global_load_ushort v8, v[10:11], off offset:2048
	global_load_ushort v8, v[10:11], off offset:3072
	v_lshl_add_u64 v[10:11], v[10:11], 0, s[16:17]
	global_load_ushort v8, v[10:11], off offset:-4096
	global_load_ushort v8, v[10:11], off offset:-3072
	global_load_ushort v8, v[10:11], off offset:-2048
	global_load_ushort v8, v[10:11], off offset:-1024
	global_load_ushort v8, v[10:11], off
	global_load_ushort v8, v[10:11], off offset:1024
	global_load_ushort v8, v[10:11], off offset:2048
	global_load_ushort v8, v[10:11], off offset:3072
	v_lshl_add_u64 v[10:11], v[10:11], 0, s[16:17]
	global_load_ushort v8, v[10:11], off offset:-4096
	global_load_ushort v8, v[10:11], off offset:-3072
	global_load_ushort v8, v[10:11], off offset:-2048
	global_load_ushort v8, v[10:11], off offset:-1024
	global_load_ushort v8, v[10:11], off
	global_load_ushort v8, v[10:11], off offset:1024
	global_load_ushort v8, v[10:11], off offset:2048
	global_load_ushort v8, v[10:11], off offset:3072
	v_lshl_add_u64 v[10:11], v[10:11], 0, s[16:17]
	global_load_ushort v8, v[10:11], off offset:-4096
	global_load_ushort v8, v[10:11], off offset:-3072
	global_load_ushort v8, v[10:11], off offset:-2048
	global_load_ushort v8, v[10:11], off offset:-1024
	global_load_ushort v8, v[10:11], off
	global_load_ushort v8, v[10:11], off offset:1024
	global_load_ushort v8, v[10:11], off offset:2048
	global_load_ushort v8, v[10:11], off offset:3072
	v_lshl_add_u64 v[10:11], v[10:11], 0, s[16:17]
	global_load_ushort v8, v[10:11], off offset:-4096
	global_load_ushort v8, v[10:11], off offset:-3072
	global_load_ushort v8, v[10:11], off offset:-2048
	global_load_ushort v8, v[10:11], off offset:-1024
	global_load_ushort v8, v[10:11], off
	global_load_ushort v8, v[10:11], off offset:1024
	global_load_ushort v8, v[10:11], off offset:2048
	global_load_ushort v8, v[10:11], off offset:3072
	v_lshl_add_u64 v[10:11], v[10:11], 0, s[16:17]
	global_load_ushort v8, v[10:11], off offset:-4096
	global_load_ushort v8, v[10:11], off offset:-3072
	global_load_ushort v8, v[10:11], off offset:-2048
	global_load_ushort v8, v[10:11], off offset:-1024
	global_load_ushort v8, v[10:11], off
	global_load_ushort v8, v[10:11], off offset:1024
	global_load_ushort v8, v[10:11], off offset:2048
	global_load_ushort v8, v[10:11], off offset:3072
	v_lshl_add_u64 v[10:11], v[10:11], 0, s[16:17]
	global_load_ushort v8, v[10:11], off offset:-4096
	global_load_ushort v8, v[10:11], off offset:-3072
	global_load_ushort v8, v[10:11], off offset:-2048
	global_load_ushort v8, v[10:11], off offset:-1024
	global_load_ushort v8, v[10:11], off
	global_load_ushort v8, v[10:11], off offset:1024
	global_load_ushort v8, v[10:11], off offset:2048
	global_load_ushort v8, v[10:11], off offset:3072
	v_lshl_add_u64 v[10:11], v[10:11], 0, s[16:17]
	global_load_ushort v8, v[10:11], off offset:-4096
	global_load_ushort v8, v[10:11], off offset:-3072
	global_load_ushort v8, v[10:11], off offset:-2048
	global_load_ushort v8, v[10:11], off offset:-1024
.Lcpf_skip:
	v_cndmask_b32_e64 v3, 0, 1, s[14:15]
	v_cmp_ne_u32_e64 s[10:11], 1, v3
	s_andn2_b64 vcc, exec, s[14:15]
	v_mov_b32_e32 v3, 0
	v_readlane_b32 s25, v252, 19
	v_readlane_b32 s26, v252, 20
	v_readlane_b32 s27, v252, 21
	v_readlane_b32 s28, v252, 22
	v_readlane_b32 s29, v252, 23
	v_readlane_b32 s30, v252, 24
	v_readlane_b32 s31, v252, 25
	s_cbranch_vccnz .LBB0_351
	v_readlane_b32 s16, v254, 53
	v_readlane_b32 s17, v254, 54
	s_nop 1
	v_lshl_add_u64 v[10:11], v[4:5], 0, s[16:17]
	global_load_ushort v3, v[10:11], off offset:1024
	global_load_ushort v9, v[10:11], off
	s_waitcnt vmcnt(1)
	v_lshlrev_b32_e32 v3, 16, v3
	v_mul_f32_e32 v3, 0xbfb8aa3b, v3
	v_exp_f32_e32 v3, v3
	s_waitcnt vmcnt(0)
	v_lshlrev_b32_e32 v9, 16, v9
	v_add_f32_e32 v3, 1.0, v3
	v_div_scale_f32 v10, s[72:73], v3, v3, 1.0
	v_rcp_f32_e32 v11, v10
	v_div_scale_f32 v12, vcc, 1.0, v3, 1.0
	v_fma_f32 v13, -v10, v11, 1.0
	v_fmac_f32_e32 v11, v13, v11
	v_mul_f32_e32 v13, v12, v11
	v_fma_f32 v14, -v10, v13, v12
	v_fmac_f32_e32 v13, v14, v11
	v_fma_f32 v10, -v10, v13, v12
	v_div_fmas_f32 v10, v10, v11, v13
	v_div_fixup_f32 v3, v10, v3, 1.0
	v_mul_f32_e32 v3, v3, v9
